# conversion-phase load balance: down and pp jobs start dealing items at the wave where the previous job's remainder ended (low waves no longer collect every remainder item) - on top of v73
# baseline (speedup 1.0000x reference)
.LBB0_153:
	s_mov_b64 s[8:9], s[96:97]
	s_mov_b32 s98, s53
	s_cmp_lg_u32 s94, 0x100
	s_cbranch_scc1 .Lmy_rot_d
	s_add_i32 s98, s53, 0x500
	s_and_b32 s98, s98, 0x7ff
.Lmy_rot_d:
	s_cmpk_gt_i32 s98, 0x157f
	s_cbranch_scc1 .LBB0_158
	s_load_dwordx2 s[2:3], s[8:9], 0xf0
	v_readlane_b32 s8, v253, 35
	s_mul_i32 s7, s8, 0x2b00000
	s_mul_hi_u32 s0, s8, 0x2b00000
	v_lshlrev_b32_e32 v22, 1, v42
	s_waitcnt lgkmcnt(0)
	s_add_u32 s2, s2, s7
	s_addc_u32 s3, s3, s0
	v_mov_b32_e32 v23, v225
	v_mul_u32_u24_e32 v1, 0x84, v42
	v_lshl_add_u64 v[20:21], s[2:3], 0, v[224:225]
	v_lshl_add_u64 v[22:23], s[40:41], 0, v[22:23]
	s_mov_b64 s[2:3], 0x8c00000
	v_add_u32_e32 v18, s54, v224
	v_lshl_add_u64 v[22:23], v[22:23], 0, s[2:3]
	v_add3_u32 v43, s54, v1, v39
	v_mov_b32_e32 v1, v2
	v_mov_b32_e32 v3, v4
	v_mov_b32_e32 v5, v6
	v_mov_b32_e32 v7, v8
	v_mov_b32_e32 v9, v10
	v_mov_b32_e32 v11, v12
	v_mov_b32_e32 v13, v14
	v_mov_b32_e32 v15, v16
	s_mov_b32 s0, s98
	v_readlane_b32 s9, v253, 36

.LBB0_158:
	s_mov_b64 s[8:9], s[96:97]
	s_mov_b32 s98, s53
	s_cmp_lg_u32 s94, 0x100
	s_cbranch_scc1 .Lmy_rot_p
	s_add_i32 s98, s53, 0x780
	s_and_b32 s98, s98, 0x7ff
.Lmy_rot_p:
	s_cmpk_gt_i32 s98, 0xff
	s_cbranch_scc1 .LBB0_163
	s_load_dwordx2 s[2:3], s[8:9], 0xf8
	v_readlane_b32 s8, v253, 35
	v_readlane_b32 s9, v253, 36
	s_lshl_b64 s[8:9], s[8:9], 21
	v_lshlrev_b32_e32 v22, 1, v42
	s_waitcnt lgkmcnt(0)
	s_add_u32 s2, s2, s8
	s_addc_u32 s3, s3, s9
	v_mov_b32_e32 v23, v225
	v_mul_u32_u24_e32 v1, 0x84, v42
	v_lshl_add_u64 v[20:21], s[2:3], 0, v[224:225]
	v_lshl_add_u64 v[22:23], s[40:41], 0, v[22:23]
	s_mov_b64 s[2:3], 0xa200000
	v_add_u32_e32 v18, s54, v224
	v_lshl_add_u64 v[22:23], v[22:23], 0, s[2:3]
	v_add3_u32 v43, s54, v1, v39
	v_mov_b32_e32 v1, v2
	v_mov_b32_e32 v3, v4
	v_mov_b32_e32 v5, v6
	v_mov_b32_e32 v7, v8
	v_mov_b32_e32 v9, v10
	v_mov_b32_e32 v11, v12
	v_mov_b32_e32 v13, v14
	v_mov_b32_e32 v15, v16
	s_mov_b32 s0, s98
